# tile header zeroed the 128 accumulators twice (before the no-K-iterations skip branch and again in the loop preheader): first block moved onto the skip path, 127 fewer VALU per tile per wave, all 8 GE
# speedup vs baseline: 1.0026x; 1.0021x over previous
.LBB0_315:
	s_ashr_i32 s27, s26, 31
	s_lshl_b64 s[0:1], s[26:27], 20
	s_add_u32 s28, s52, s0
	s_addc_u32 s29, s53, s1
	s_ashr_i32 s25, s24, 31
	s_lshl_b64 s[0:1], s[24:25], 20
	s_add_u32 s30, s50, s0
	v_mov_b32_e32 v131, 0
	s_addc_u32 s31, s51, s1
	s_andn2_b64 vcc, exec, s[10:11]
	s_cbranch_vccz .Lkz_0
	v_mov_b32_e32 v130, v131
	v_mov_b32_e32 v129, v131
	v_mov_b32_e32 v128, v131
	v_mov_b32_e32 v127, v131
	v_mov_b32_e32 v126, v131
	v_mov_b32_e32 v125, v131
	v_mov_b32_e32 v124, v131
	v_mov_b32_e32 v115, v131
	v_mov_b32_e32 v114, v131
	v_mov_b32_e32 v113, v131
	v_mov_b32_e32 v112, v131
	v_mov_b32_e32 v111, v131
	v_mov_b32_e32 v110, v131
	v_mov_b32_e32 v109, v131
	v_mov_b32_e32 v108, v131
	v_mov_b32_e32 v99, v131
	v_mov_b32_e32 v98, v131
	v_mov_b32_e32 v97, v131
	v_mov_b32_e32 v96, v131
	v_mov_b32_e32 v95, v131
	v_mov_b32_e32 v94, v131
	v_mov_b32_e32 v93, v131
	v_mov_b32_e32 v92, v131
	v_mov_b32_e32 v83, v131
	v_mov_b32_e32 v82, v131
	v_mov_b32_e32 v81, v131
	v_mov_b32_e32 v80, v131
	v_mov_b32_e32 v79, v131
	v_mov_b32_e32 v78, v131
	v_mov_b32_e32 v77, v131
	v_mov_b32_e32 v76, v131
	v_mov_b32_e32 v123, v131
	v_mov_b32_e32 v122, v131
	v_mov_b32_e32 v121, v131
	v_mov_b32_e32 v120, v131
	v_mov_b32_e32 v119, v131
	v_mov_b32_e32 v118, v131
	v_mov_b32_e32 v117, v131
	v_mov_b32_e32 v116, v131
	v_mov_b32_e32 v107, v131
	v_mov_b32_e32 v106, v131
	v_mov_b32_e32 v105, v131
	v_mov_b32_e32 v104, v131
	v_mov_b32_e32 v103, v131
	v_mov_b32_e32 v102, v131
	v_mov_b32_e32 v101, v131
	v_mov_b32_e32 v100, v131
	v_mov_b32_e32 v91, v131
	v_mov_b32_e32 v90, v131
	v_mov_b32_e32 v89, v131
	v_mov_b32_e32 v88, v131
	v_mov_b32_e32 v87, v131
	v_mov_b32_e32 v86, v131
	v_mov_b32_e32 v85, v131
	v_mov_b32_e32 v84, v131
	v_mov_b32_e32 v75, v131
	v_mov_b32_e32 v74, v131
	v_mov_b32_e32 v73, v131
	v_mov_b32_e32 v72, v131
	v_mov_b32_e32 v71, v131
	v_mov_b32_e32 v70, v131
	v_mov_b32_e32 v69, v131
	v_mov_b32_e32 v68, v131
	v_mov_b32_e32 v67, v131
	v_mov_b32_e32 v66, v131
	v_mov_b32_e32 v65, v131
	v_mov_b32_e32 v64, v131
	v_mov_b32_e32 v63, v131
	v_mov_b32_e32 v62, v131
	v_mov_b32_e32 v61, v131
	v_mov_b32_e32 v60, v131
	v_mov_b32_e32 v51, v131
	v_mov_b32_e32 v50, v131
	v_mov_b32_e32 v49, v131
	v_mov_b32_e32 v48, v131
	v_mov_b32_e32 v47, v131
	v_mov_b32_e32 v46, v131
	v_mov_b32_e32 v45, v131
	v_mov_b32_e32 v44, v131
	v_mov_b32_e32 v35, v131
	v_mov_b32_e32 v34, v131
	v_mov_b32_e32 v33, v131
	v_mov_b32_e32 v32, v131
	v_mov_b32_e32 v31, v131
	v_mov_b32_e32 v30, v131
	v_mov_b32_e32 v29, v131
	v_mov_b32_e32 v28, v131
	v_mov_b32_e32 v19, v131
	v_mov_b32_e32 v18, v131
	v_mov_b32_e32 v17, v131
	v_mov_b32_e32 v16, v131
	v_mov_b32_e32 v15, v131
	v_mov_b32_e32 v14, v131
	v_mov_b32_e32 v13, v131
	v_mov_b32_e32 v12, v131
	v_mov_b32_e32 v59, v131
	v_mov_b32_e32 v58, v131
	v_mov_b32_e32 v57, v131
	v_mov_b32_e32 v56, v131
	v_mov_b32_e32 v55, v131
	v_mov_b32_e32 v54, v131
	v_mov_b32_e32 v53, v131
	v_mov_b32_e32 v52, v131
	v_mov_b32_e32 v43, v131
	v_mov_b32_e32 v42, v131
	v_mov_b32_e32 v41, v131
	v_mov_b32_e32 v40, v131
	v_mov_b32_e32 v39, v131
	v_mov_b32_e32 v38, v131
	v_mov_b32_e32 v37, v131
	v_mov_b32_e32 v36, v131
	v_mov_b32_e32 v27, v131
	v_mov_b32_e32 v26, v131
	v_mov_b32_e32 v25, v131
	v_mov_b32_e32 v24, v131
	v_mov_b32_e32 v23, v131
	v_mov_b32_e32 v22, v131
	v_mov_b32_e32 v21, v131
	v_mov_b32_e32 v20, v131
	v_mov_b32_e32 v11, v131
	v_mov_b32_e32 v10, v131
	v_mov_b32_e32 v9, v131
	v_mov_b32_e32 v8, v131
	v_mov_b32_e32 v7, v131
	v_mov_b32_e32 v6, v131
	v_mov_b32_e32 v5, v131
	v_mov_b32_e32 v4, v131
	s_branch .LBB0_318
.Lkz_0:
	s_and_b64 s[0:1], s[38:39], exec
	s_cselect_b32 s0, s29, s41
	s_cselect_b32 s1, s28, s40
	s_cselect_b32 s5, s31, s3
	s_cselect_b32 s7, s30, s2
	s_add_u32 s14, s40, 0x100
	s_addc_u32 s15, s41, 0
	s_add_u32 s25, s2, 0x100
	v_mov_b32_e32 v4, 0
	s_addc_u32 s27, s3, 0
	s_mov_b32 s2, 0
	v_mov_b32_e32 v5, v4
	v_mov_b32_e32 v6, v4
	v_mov_b32_e32 v7, v4
	v_mov_b32_e32 v8, v4
	v_mov_b32_e32 v9, v4
	v_mov_b32_e32 v10, v4
	v_mov_b32_e32 v11, v4
	v_mov_b32_e32 v20, v4
	v_mov_b32_e32 v21, v4
	v_mov_b32_e32 v22, v4
	v_mov_b32_e32 v23, v4
	v_mov_b32_e32 v24, v4
	v_mov_b32_e32 v25, v4
	v_mov_b32_e32 v26, v4
	v_mov_b32_e32 v27, v4
	v_mov_b32_e32 v36, v4
	v_mov_b32_e32 v37, v4
	v_mov_b32_e32 v38, v4
	v_mov_b32_e32 v39, v4
	v_mov_b32_e32 v40, v4
	v_mov_b32_e32 v41, v4
	v_mov_b32_e32 v42, v4
	v_mov_b32_e32 v43, v4
	v_mov_b32_e32 v52, v4
	v_mov_b32_e32 v53, v4
	v_mov_b32_e32 v54, v4
	v_mov_b32_e32 v55, v4
	v_mov_b32_e32 v56, v4
	v_mov_b32_e32 v57, v4
	v_mov_b32_e32 v58, v4
	v_mov_b32_e32 v59, v4
	v_mov_b32_e32 v12, v4
	v_mov_b32_e32 v13, v4
	v_mov_b32_e32 v14, v4
	v_mov_b32_e32 v15, v4
	v_mov_b32_e32 v16, v4
	v_mov_b32_e32 v17, v4
	v_mov_b32_e32 v18, v4
	v_mov_b32_e32 v19, v4
	v_mov_b32_e32 v28, v4
	v_mov_b32_e32 v29, v4
	v_mov_b32_e32 v30, v4
	v_mov_b32_e32 v31, v4
	v_mov_b32_e32 v32, v4
	v_mov_b32_e32 v33, v4
	v_mov_b32_e32 v34, v4
	v_mov_b32_e32 v35, v4
	v_mov_b32_e32 v44, v4
	v_mov_b32_e32 v45, v4
	v_mov_b32_e32 v46, v4
	v_mov_b32_e32 v47, v4
	v_mov_b32_e32 v48, v4
	v_mov_b32_e32 v49, v4
	v_mov_b32_e32 v50, v4
	v_mov_b32_e32 v51, v4
	v_mov_b32_e32 v60, v4
	v_mov_b32_e32 v61, v4
	v_mov_b32_e32 v62, v4
	v_mov_b32_e32 v63, v4
	v_mov_b32_e32 v64, v4
	v_mov_b32_e32 v65, v4
	v_mov_b32_e32 v66, v4
	v_mov_b32_e32 v67, v4
	v_mov_b32_e32 v68, v4
	v_mov_b32_e32 v69, v4
	v_mov_b32_e32 v70, v4
	v_mov_b32_e32 v71, v4
	v_mov_b32_e32 v72, v4
	v_mov_b32_e32 v73, v4
	v_mov_b32_e32 v74, v4
	v_mov_b32_e32 v75, v4
	v_mov_b32_e32 v84, v4
	v_mov_b32_e32 v85, v4
	v_mov_b32_e32 v86, v4
	v_mov_b32_e32 v87, v4
	v_mov_b32_e32 v88, v4
	v_mov_b32_e32 v89, v4
	v_mov_b32_e32 v90, v4
	v_mov_b32_e32 v91, v4
	v_mov_b32_e32 v100, v4
	v_mov_b32_e32 v101, v4
	v_mov_b32_e32 v102, v4
	v_mov_b32_e32 v103, v4
	v_mov_b32_e32 v104, v4
	v_mov_b32_e32 v105, v4
	v_mov_b32_e32 v106, v4
	v_mov_b32_e32 v107, v4
	v_mov_b32_e32 v116, v4
	v_mov_b32_e32 v117, v4
	v_mov_b32_e32 v118, v4
	v_mov_b32_e32 v119, v4
	v_mov_b32_e32 v120, v4
	v_mov_b32_e32 v121, v4
	v_mov_b32_e32 v122, v4
	v_mov_b32_e32 v123, v4
	v_mov_b32_e32 v76, v4
	v_mov_b32_e32 v77, v4
	v_mov_b32_e32 v78, v4
	v_mov_b32_e32 v79, v4
	v_mov_b32_e32 v80, v4
	v_mov_b32_e32 v81, v4
	v_mov_b32_e32 v82, v4
	v_mov_b32_e32 v83, v4
	v_mov_b32_e32 v92, v4
	v_mov_b32_e32 v93, v4
	v_mov_b32_e32 v94, v4
	v_mov_b32_e32 v95, v4
	v_mov_b32_e32 v96, v4
	v_mov_b32_e32 v97, v4
	v_mov_b32_e32 v98, v4
	v_mov_b32_e32 v99, v4
	v_mov_b32_e32 v108, v4
	v_mov_b32_e32 v109, v4
	v_mov_b32_e32 v110, v4
	v_mov_b32_e32 v111, v4
	v_mov_b32_e32 v112, v4
	v_mov_b32_e32 v113, v4
	v_mov_b32_e32 v114, v4
	v_mov_b32_e32 v115, v4
	v_mov_b32_e32 v124, v4
	v_mov_b32_e32 v125, v4
	v_mov_b32_e32 v126, v4
	v_mov_b32_e32 v127, v4
	v_mov_b32_e32 v128, v4
	v_mov_b32_e32 v129, v4
	v_mov_b32_e32 v130, v4
	v_mov_b32_e32 v131, v4

.LBB0_586:
	s_ashr_i32 s29, s28, 31
	s_lshl_b64 s[30:31], s[28:29], 18
	s_add_u32 s30, s0, s30
	s_addc_u32 s31, s1, s31
	s_ashr_i32 s27, s26, 31
	s_lshl_b64 s[38:39], s[26:27], 18
	s_add_u32 s38, s14, s38
	v_mov_b32_e32 v127, 0
	s_addc_u32 s39, s15, s39
	s_andn2_b64 vcc, exec, s[22:23]
	s_cbranch_vccz .Lkz_1
	v_mov_b32_e32 v126, v127
	v_mov_b32_e32 v125, v127
	v_mov_b32_e32 v124, v127
	v_mov_b32_e32 v131, v127
	v_mov_b32_e32 v130, v127
	v_mov_b32_e32 v129, v127
	v_mov_b32_e32 v128, v127
	v_mov_b32_e32 v115, v127
	v_mov_b32_e32 v114, v127
	v_mov_b32_e32 v113, v127
	v_mov_b32_e32 v112, v127
	v_mov_b32_e32 v111, v127
	v_mov_b32_e32 v110, v127
	v_mov_b32_e32 v109, v127
	v_mov_b32_e32 v108, v127
	v_mov_b32_e32 v99, v127
	v_mov_b32_e32 v98, v127
	v_mov_b32_e32 v97, v127
	v_mov_b32_e32 v96, v127
	v_mov_b32_e32 v95, v127
	v_mov_b32_e32 v94, v127
	v_mov_b32_e32 v93, v127
	v_mov_b32_e32 v92, v127
	v_mov_b32_e32 v83, v127
	v_mov_b32_e32 v82, v127
	v_mov_b32_e32 v81, v127
	v_mov_b32_e32 v80, v127
	v_mov_b32_e32 v79, v127
	v_mov_b32_e32 v78, v127
	v_mov_b32_e32 v77, v127
	v_mov_b32_e32 v76, v127
	v_mov_b32_e32 v123, v127
	v_mov_b32_e32 v122, v127
	v_mov_b32_e32 v121, v127
	v_mov_b32_e32 v120, v127
	v_mov_b32_e32 v119, v127
	v_mov_b32_e32 v118, v127
	v_mov_b32_e32 v117, v127
	v_mov_b32_e32 v116, v127
	v_mov_b32_e32 v107, v127
	v_mov_b32_e32 v106, v127
	v_mov_b32_e32 v105, v127
	v_mov_b32_e32 v104, v127
	v_mov_b32_e32 v103, v127
	v_mov_b32_e32 v102, v127
	v_mov_b32_e32 v101, v127
	v_mov_b32_e32 v100, v127
	v_mov_b32_e32 v91, v127
	v_mov_b32_e32 v90, v127
	v_mov_b32_e32 v89, v127
	v_mov_b32_e32 v88, v127
	v_mov_b32_e32 v87, v127
	v_mov_b32_e32 v86, v127
	v_mov_b32_e32 v85, v127
	v_mov_b32_e32 v84, v127
	v_mov_b32_e32 v75, v127
	v_mov_b32_e32 v74, v127
	v_mov_b32_e32 v73, v127
	v_mov_b32_e32 v72, v127
	v_mov_b32_e32 v71, v127
	v_mov_b32_e32 v70, v127
	v_mov_b32_e32 v69, v127
	v_mov_b32_e32 v68, v127
	v_mov_b32_e32 v67, v127
	v_mov_b32_e32 v66, v127
	v_mov_b32_e32 v65, v127
	v_mov_b32_e32 v64, v127
	v_mov_b32_e32 v63, v127
	v_mov_b32_e32 v62, v127
	v_mov_b32_e32 v61, v127
	v_mov_b32_e32 v60, v127
	v_mov_b32_e32 v51, v127
	v_mov_b32_e32 v50, v127
	v_mov_b32_e32 v49, v127
	v_mov_b32_e32 v48, v127
	v_mov_b32_e32 v47, v127
	v_mov_b32_e32 v46, v127
	v_mov_b32_e32 v45, v127
	v_mov_b32_e32 v44, v127
	v_mov_b32_e32 v35, v127
	v_mov_b32_e32 v34, v127
	v_mov_b32_e32 v33, v127
	v_mov_b32_e32 v32, v127
	v_mov_b32_e32 v31, v127
	v_mov_b32_e32 v30, v127
	v_mov_b32_e32 v29, v127
	v_mov_b32_e32 v28, v127
	v_mov_b32_e32 v19, v127
	v_mov_b32_e32 v18, v127
	v_mov_b32_e32 v17, v127
	v_mov_b32_e32 v16, v127
	v_mov_b32_e32 v15, v127
	v_mov_b32_e32 v14, v127
	v_mov_b32_e32 v13, v127
	v_mov_b32_e32 v12, v127
	v_mov_b32_e32 v59, v127
	v_mov_b32_e32 v58, v127
	v_mov_b32_e32 v57, v127
	v_mov_b32_e32 v56, v127
	v_mov_b32_e32 v55, v127
	v_mov_b32_e32 v54, v127
	v_mov_b32_e32 v53, v127
	v_mov_b32_e32 v52, v127
	v_mov_b32_e32 v43, v127
	v_mov_b32_e32 v42, v127
	v_mov_b32_e32 v41, v127
	v_mov_b32_e32 v40, v127
	v_mov_b32_e32 v39, v127
	v_mov_b32_e32 v38, v127
	v_mov_b32_e32 v37, v127
	v_mov_b32_e32 v36, v127
	v_mov_b32_e32 v27, v127
	v_mov_b32_e32 v26, v127
	v_mov_b32_e32 v25, v127
	v_mov_b32_e32 v24, v127
	v_mov_b32_e32 v23, v127
	v_mov_b32_e32 v22, v127
	v_mov_b32_e32 v21, v127
	v_mov_b32_e32 v20, v127
	v_mov_b32_e32 v11, v127
	v_mov_b32_e32 v10, v127
	v_mov_b32_e32 v9, v127
	v_mov_b32_e32 v8, v127
	v_mov_b32_e32 v7, v127
	v_mov_b32_e32 v6, v127
	v_mov_b32_e32 v5, v127
	v_mov_b32_e32 v4, v127
	s_branch .LBB0_589
.Lkz_1:
	s_and_b64 s[48:49], s[4:5], exec
	s_cselect_b32 s27, s31, s43
	s_cselect_b32 s29, s30, s42
	s_cselect_b32 s73, s39, s41
	s_cselect_b32 s74, s38, s40
	s_add_u32 s75, s42, 0x100
	s_addc_u32 s76, s43, 0
	s_add_u32 s77, s40, 0x100
	s_addc_u32 s78, s41, 0
	s_add_u32 s40, s42, 0x20080
	v_mov_b32_e32 v4, 0
	s_addc_u32 s41, s43, 0
	s_mov_b32 s42, 0
	v_mov_b32_e32 v5, v4
	v_mov_b32_e32 v6, v4
	v_mov_b32_e32 v7, v4
	v_mov_b32_e32 v8, v4
	v_mov_b32_e32 v9, v4
	v_mov_b32_e32 v10, v4
	v_mov_b32_e32 v11, v4
	v_mov_b32_e32 v20, v4
	v_mov_b32_e32 v21, v4
	v_mov_b32_e32 v22, v4
	v_mov_b32_e32 v23, v4
	v_mov_b32_e32 v24, v4
	v_mov_b32_e32 v25, v4
	v_mov_b32_e32 v26, v4
	v_mov_b32_e32 v27, v4
	v_mov_b32_e32 v36, v4
	v_mov_b32_e32 v37, v4
	v_mov_b32_e32 v38, v4
	v_mov_b32_e32 v39, v4
	v_mov_b32_e32 v40, v4
	v_mov_b32_e32 v41, v4
	v_mov_b32_e32 v42, v4
	v_mov_b32_e32 v43, v4
	v_mov_b32_e32 v52, v4
	v_mov_b32_e32 v53, v4
	v_mov_b32_e32 v54, v4
	v_mov_b32_e32 v55, v4
	v_mov_b32_e32 v56, v4
	v_mov_b32_e32 v57, v4
	v_mov_b32_e32 v58, v4
	v_mov_b32_e32 v59, v4
	v_mov_b32_e32 v12, v4
	v_mov_b32_e32 v13, v4
	v_mov_b32_e32 v14, v4
	v_mov_b32_e32 v15, v4
	v_mov_b32_e32 v16, v4
	v_mov_b32_e32 v17, v4
	v_mov_b32_e32 v18, v4
	v_mov_b32_e32 v19, v4
	v_mov_b32_e32 v28, v4
	v_mov_b32_e32 v29, v4
	v_mov_b32_e32 v30, v4
	v_mov_b32_e32 v31, v4
	v_mov_b32_e32 v32, v4
	v_mov_b32_e32 v33, v4
	v_mov_b32_e32 v34, v4
	v_mov_b32_e32 v35, v4
	v_mov_b32_e32 v44, v4
	v_mov_b32_e32 v45, v4
	v_mov_b32_e32 v46, v4
	v_mov_b32_e32 v47, v4
	v_mov_b32_e32 v48, v4
	v_mov_b32_e32 v49, v4
	v_mov_b32_e32 v50, v4
	v_mov_b32_e32 v51, v4
	v_mov_b32_e32 v60, v4
	v_mov_b32_e32 v61, v4
	v_mov_b32_e32 v62, v4
	v_mov_b32_e32 v63, v4
	v_mov_b32_e32 v64, v4
	v_mov_b32_e32 v65, v4
	v_mov_b32_e32 v66, v4
	v_mov_b32_e32 v67, v4
	v_mov_b32_e32 v68, v4
	v_mov_b32_e32 v69, v4
	v_mov_b32_e32 v70, v4
	v_mov_b32_e32 v71, v4
	v_mov_b32_e32 v72, v4
	v_mov_b32_e32 v73, v4
	v_mov_b32_e32 v74, v4
	v_mov_b32_e32 v75, v4
	v_mov_b32_e32 v84, v4
	v_mov_b32_e32 v85, v4
	v_mov_b32_e32 v86, v4
	v_mov_b32_e32 v87, v4
	v_mov_b32_e32 v88, v4
	v_mov_b32_e32 v89, v4
	v_mov_b32_e32 v90, v4
	v_mov_b32_e32 v91, v4
	v_mov_b32_e32 v100, v4
	v_mov_b32_e32 v101, v4
	v_mov_b32_e32 v102, v4
	v_mov_b32_e32 v103, v4
	v_mov_b32_e32 v104, v4
	v_mov_b32_e32 v105, v4
	v_mov_b32_e32 v106, v4
	v_mov_b32_e32 v107, v4
	v_mov_b32_e32 v116, v4
	v_mov_b32_e32 v117, v4
	v_mov_b32_e32 v118, v4
	v_mov_b32_e32 v119, v4
	v_mov_b32_e32 v120, v4
	v_mov_b32_e32 v121, v4
	v_mov_b32_e32 v122, v4
	v_mov_b32_e32 v123, v4
	v_mov_b32_e32 v76, v4
	v_mov_b32_e32 v77, v4
	v_mov_b32_e32 v78, v4
	v_mov_b32_e32 v79, v4
	v_mov_b32_e32 v80, v4
	v_mov_b32_e32 v81, v4
	v_mov_b32_e32 v82, v4
	v_mov_b32_e32 v83, v4
	v_mov_b32_e32 v92, v4
	v_mov_b32_e32 v93, v4
	v_mov_b32_e32 v94, v4
	v_mov_b32_e32 v95, v4
	v_mov_b32_e32 v96, v4
	v_mov_b32_e32 v97, v4
	v_mov_b32_e32 v98, v4
	v_mov_b32_e32 v99, v4
	v_mov_b32_e32 v108, v4
	v_mov_b32_e32 v109, v4
	v_mov_b32_e32 v110, v4
	v_mov_b32_e32 v111, v4
	v_mov_b32_e32 v112, v4
	v_mov_b32_e32 v113, v4
	v_mov_b32_e32 v114, v4
	v_mov_b32_e32 v115, v4
	v_mov_b32_e32 v128, v4
	v_mov_b32_e32 v129, v4
	v_mov_b32_e32 v130, v4
	v_mov_b32_e32 v131, v4
	v_mov_b32_e32 v124, v4
	v_mov_b32_e32 v125, v4
	v_mov_b32_e32 v126, v4
	v_mov_b32_e32 v127, v4

.LBB0_603:
	s_ashr_i32 s3, s2, 31
	s_lshl_b64 s[30:31], s[2:3], 17
	s_add_u32 s30, s1, s30
	s_addc_u32 s31, s14, s31
	s_ashr_i32 s27, s26, 31
	s_lshl_b64 s[38:39], s[26:27], 17
	s_add_u32 s38, s15, s38
	v_mov_b32_e32 v127, 0
	s_addc_u32 s39, s33, s39
	s_andn2_b64 vcc, exec, s[22:23]
	s_cbranch_vccz .Lkz_2
	v_mov_b32_e32 v126, v127
	v_mov_b32_e32 v125, v127
	v_mov_b32_e32 v124, v127
	v_mov_b32_e32 v131, v127
	v_mov_b32_e32 v130, v127
	v_mov_b32_e32 v129, v127
	v_mov_b32_e32 v128, v127
	v_mov_b32_e32 v115, v127
	v_mov_b32_e32 v114, v127
	v_mov_b32_e32 v113, v127
	v_mov_b32_e32 v112, v127
	v_mov_b32_e32 v111, v127
	v_mov_b32_e32 v110, v127
	v_mov_b32_e32 v109, v127
	v_mov_b32_e32 v108, v127
	v_mov_b32_e32 v99, v127
	v_mov_b32_e32 v98, v127
	v_mov_b32_e32 v97, v127
	v_mov_b32_e32 v96, v127
	v_mov_b32_e32 v95, v127
	v_mov_b32_e32 v94, v127
	v_mov_b32_e32 v93, v127
	v_mov_b32_e32 v92, v127
	v_mov_b32_e32 v83, v127
	v_mov_b32_e32 v82, v127
	v_mov_b32_e32 v81, v127
	v_mov_b32_e32 v80, v127
	v_mov_b32_e32 v79, v127
	v_mov_b32_e32 v78, v127
	v_mov_b32_e32 v77, v127
	v_mov_b32_e32 v76, v127
	v_mov_b32_e32 v123, v127
	v_mov_b32_e32 v122, v127
	v_mov_b32_e32 v121, v127
	v_mov_b32_e32 v120, v127
	v_mov_b32_e32 v119, v127
	v_mov_b32_e32 v118, v127
	v_mov_b32_e32 v117, v127
	v_mov_b32_e32 v116, v127
	v_mov_b32_e32 v107, v127
	v_mov_b32_e32 v106, v127
	v_mov_b32_e32 v105, v127
	v_mov_b32_e32 v104, v127
	v_mov_b32_e32 v103, v127
	v_mov_b32_e32 v102, v127
	v_mov_b32_e32 v101, v127
	v_mov_b32_e32 v100, v127
	v_mov_b32_e32 v91, v127
	v_mov_b32_e32 v90, v127
	v_mov_b32_e32 v89, v127
	v_mov_b32_e32 v88, v127
	v_mov_b32_e32 v87, v127
	v_mov_b32_e32 v86, v127
	v_mov_b32_e32 v85, v127
	v_mov_b32_e32 v84, v127
	v_mov_b32_e32 v75, v127
	v_mov_b32_e32 v74, v127
	v_mov_b32_e32 v73, v127
	v_mov_b32_e32 v72, v127
	v_mov_b32_e32 v71, v127
	v_mov_b32_e32 v70, v127
	v_mov_b32_e32 v69, v127
	v_mov_b32_e32 v68, v127
	v_mov_b32_e32 v67, v127
	v_mov_b32_e32 v66, v127
	v_mov_b32_e32 v65, v127
	v_mov_b32_e32 v64, v127
	v_mov_b32_e32 v63, v127
	v_mov_b32_e32 v62, v127
	v_mov_b32_e32 v61, v127
	v_mov_b32_e32 v60, v127
	v_mov_b32_e32 v51, v127
	v_mov_b32_e32 v50, v127
	v_mov_b32_e32 v49, v127
	v_mov_b32_e32 v48, v127
	v_mov_b32_e32 v47, v127
	v_mov_b32_e32 v46, v127
	v_mov_b32_e32 v45, v127
	v_mov_b32_e32 v44, v127
	v_mov_b32_e32 v35, v127
	v_mov_b32_e32 v34, v127
	v_mov_b32_e32 v33, v127
	v_mov_b32_e32 v32, v127
	v_mov_b32_e32 v31, v127
	v_mov_b32_e32 v30, v127
	v_mov_b32_e32 v29, v127
	v_mov_b32_e32 v28, v127
	v_mov_b32_e32 v19, v127
	v_mov_b32_e32 v18, v127
	v_mov_b32_e32 v17, v127
	v_mov_b32_e32 v16, v127
	v_mov_b32_e32 v15, v127
	v_mov_b32_e32 v14, v127
	v_mov_b32_e32 v13, v127
	v_mov_b32_e32 v12, v127
	v_mov_b32_e32 v59, v127
	v_mov_b32_e32 v58, v127
	v_mov_b32_e32 v57, v127
	v_mov_b32_e32 v56, v127
	v_mov_b32_e32 v55, v127
	v_mov_b32_e32 v54, v127
	v_mov_b32_e32 v53, v127
	v_mov_b32_e32 v52, v127
	v_mov_b32_e32 v43, v127
	v_mov_b32_e32 v42, v127
	v_mov_b32_e32 v41, v127
	v_mov_b32_e32 v40, v127
	v_mov_b32_e32 v39, v127
	v_mov_b32_e32 v38, v127
	v_mov_b32_e32 v37, v127
	v_mov_b32_e32 v36, v127
	v_mov_b32_e32 v27, v127
	v_mov_b32_e32 v26, v127
	v_mov_b32_e32 v25, v127
	v_mov_b32_e32 v24, v127
	v_mov_b32_e32 v23, v127
	v_mov_b32_e32 v22, v127
	v_mov_b32_e32 v21, v127
	v_mov_b32_e32 v20, v127
	v_mov_b32_e32 v11, v127
	v_mov_b32_e32 v10, v127
	v_mov_b32_e32 v9, v127
	v_mov_b32_e32 v8, v127
	v_mov_b32_e32 v7, v127
	v_mov_b32_e32 v6, v127
	v_mov_b32_e32 v5, v127
	v_mov_b32_e32 v4, v127
	s_branch .LBB0_606
.Lkz_2:
	s_and_b64 s[48:49], s[4:5], exec
	s_cselect_b32 s3, s31, s43
	s_cselect_b32 s27, s30, s42
	s_cselect_b32 s73, s39, s41
	s_cselect_b32 s74, s38, s40
	s_add_u32 s75, s42, 0x100
	s_addc_u32 s76, s43, 0
	s_add_u32 s77, s40, 0x100
	s_addc_u32 s78, s41, 0
	s_add_u32 s40, s42, 0x10080
	v_mov_b32_e32 v4, 0
	s_addc_u32 s41, s43, 0
	s_mov_b32 s42, 0
	v_mov_b32_e32 v5, v4
	v_mov_b32_e32 v6, v4
	v_mov_b32_e32 v7, v4
	v_mov_b32_e32 v8, v4
	v_mov_b32_e32 v9, v4
	v_mov_b32_e32 v10, v4
	v_mov_b32_e32 v11, v4
	v_mov_b32_e32 v20, v4
	v_mov_b32_e32 v21, v4
	v_mov_b32_e32 v22, v4
	v_mov_b32_e32 v23, v4
	v_mov_b32_e32 v24, v4
	v_mov_b32_e32 v25, v4
	v_mov_b32_e32 v26, v4
	v_mov_b32_e32 v27, v4
	v_mov_b32_e32 v36, v4
	v_mov_b32_e32 v37, v4
	v_mov_b32_e32 v38, v4
	v_mov_b32_e32 v39, v4
	v_mov_b32_e32 v40, v4
	v_mov_b32_e32 v41, v4
	v_mov_b32_e32 v42, v4
	v_mov_b32_e32 v43, v4
	v_mov_b32_e32 v52, v4
	v_mov_b32_e32 v53, v4
	v_mov_b32_e32 v54, v4
	v_mov_b32_e32 v55, v4
	v_mov_b32_e32 v56, v4
	v_mov_b32_e32 v57, v4
	v_mov_b32_e32 v58, v4
	v_mov_b32_e32 v59, v4
	v_mov_b32_e32 v12, v4
	v_mov_b32_e32 v13, v4
	v_mov_b32_e32 v14, v4
	v_mov_b32_e32 v15, v4
	v_mov_b32_e32 v16, v4
	v_mov_b32_e32 v17, v4
	v_mov_b32_e32 v18, v4
	v_mov_b32_e32 v19, v4
	v_mov_b32_e32 v28, v4
	v_mov_b32_e32 v29, v4
	v_mov_b32_e32 v30, v4
	v_mov_b32_e32 v31, v4
	v_mov_b32_e32 v32, v4
	v_mov_b32_e32 v33, v4
	v_mov_b32_e32 v34, v4
	v_mov_b32_e32 v35, v4
	v_mov_b32_e32 v44, v4
	v_mov_b32_e32 v45, v4
	v_mov_b32_e32 v46, v4
	v_mov_b32_e32 v47, v4
	v_mov_b32_e32 v48, v4
	v_mov_b32_e32 v49, v4
	v_mov_b32_e32 v50, v4
	v_mov_b32_e32 v51, v4
	v_mov_b32_e32 v60, v4
	v_mov_b32_e32 v61, v4
	v_mov_b32_e32 v62, v4
	v_mov_b32_e32 v63, v4
	v_mov_b32_e32 v64, v4
	v_mov_b32_e32 v65, v4
	v_mov_b32_e32 v66, v4
	v_mov_b32_e32 v67, v4
	v_mov_b32_e32 v68, v4
	v_mov_b32_e32 v69, v4
	v_mov_b32_e32 v70, v4
	v_mov_b32_e32 v71, v4
	v_mov_b32_e32 v72, v4
	v_mov_b32_e32 v73, v4
	v_mov_b32_e32 v74, v4
	v_mov_b32_e32 v75, v4
	v_mov_b32_e32 v84, v4
	v_mov_b32_e32 v85, v4
	v_mov_b32_e32 v86, v4
	v_mov_b32_e32 v87, v4
	v_mov_b32_e32 v88, v4
	v_mov_b32_e32 v89, v4
	v_mov_b32_e32 v90, v4
	v_mov_b32_e32 v91, v4
	v_mov_b32_e32 v100, v4
	v_mov_b32_e32 v101, v4
	v_mov_b32_e32 v102, v4
	v_mov_b32_e32 v103, v4
	v_mov_b32_e32 v104, v4
	v_mov_b32_e32 v105, v4
	v_mov_b32_e32 v106, v4
	v_mov_b32_e32 v107, v4
	v_mov_b32_e32 v116, v4
	v_mov_b32_e32 v117, v4
	v_mov_b32_e32 v118, v4
	v_mov_b32_e32 v119, v4
	v_mov_b32_e32 v120, v4
	v_mov_b32_e32 v121, v4
	v_mov_b32_e32 v122, v4
	v_mov_b32_e32 v123, v4
	v_mov_b32_e32 v76, v4
	v_mov_b32_e32 v77, v4
	v_mov_b32_e32 v78, v4
	v_mov_b32_e32 v79, v4
	v_mov_b32_e32 v80, v4
	v_mov_b32_e32 v81, v4
	v_mov_b32_e32 v82, v4
	v_mov_b32_e32 v83, v4
	v_mov_b32_e32 v92, v4
	v_mov_b32_e32 v93, v4
	v_mov_b32_e32 v94, v4
	v_mov_b32_e32 v95, v4
	v_mov_b32_e32 v96, v4
	v_mov_b32_e32 v97, v4
	v_mov_b32_e32 v98, v4
	v_mov_b32_e32 v99, v4
	v_mov_b32_e32 v108, v4
	v_mov_b32_e32 v109, v4
	v_mov_b32_e32 v110, v4
	v_mov_b32_e32 v111, v4
	v_mov_b32_e32 v112, v4
	v_mov_b32_e32 v113, v4
	v_mov_b32_e32 v114, v4
	v_mov_b32_e32 v115, v4
	v_mov_b32_e32 v128, v4
	v_mov_b32_e32 v129, v4
	v_mov_b32_e32 v130, v4
	v_mov_b32_e32 v131, v4
	v_mov_b32_e32 v124, v4
	v_mov_b32_e32 v125, v4
	v_mov_b32_e32 v126, v4
	v_mov_b32_e32 v127, v4

.LBB0_620:
	s_ashr_i32 s23, s22, 31
	s_lshl_b64 s[24:25], s[22:23], 18
	s_add_u32 s24, s42, s24
	s_addc_u32 s25, s43, s25
	s_ashr_i32 s21, s20, 31
	s_lshl_b64 s[26:27], s[20:21], 18
	s_add_u32 s26, s48, s26
	v_mov_b32_e32 v127, 0
	s_addc_u32 s27, s49, s27
	s_andn2_b64 vcc, exec, s[12:13]
	s_cbranch_vccz .Lkz_3
	v_mov_b32_e32 v126, v127
	v_mov_b32_e32 v125, v127
	v_mov_b32_e32 v124, v127
	v_mov_b32_e32 v131, v127
	v_mov_b32_e32 v130, v127
	v_mov_b32_e32 v129, v127
	v_mov_b32_e32 v128, v127
	v_mov_b32_e32 v115, v127
	v_mov_b32_e32 v114, v127
	v_mov_b32_e32 v113, v127
	v_mov_b32_e32 v112, v127
	v_mov_b32_e32 v111, v127
	v_mov_b32_e32 v110, v127
	v_mov_b32_e32 v109, v127
	v_mov_b32_e32 v108, v127
	v_mov_b32_e32 v99, v127
	v_mov_b32_e32 v98, v127
	v_mov_b32_e32 v97, v127
	v_mov_b32_e32 v96, v127
	v_mov_b32_e32 v95, v127
	v_mov_b32_e32 v94, v127
	v_mov_b32_e32 v93, v127
	v_mov_b32_e32 v92, v127
	v_mov_b32_e32 v83, v127
	v_mov_b32_e32 v82, v127
	v_mov_b32_e32 v81, v127
	v_mov_b32_e32 v80, v127
	v_mov_b32_e32 v79, v127
	v_mov_b32_e32 v78, v127
	v_mov_b32_e32 v77, v127
	v_mov_b32_e32 v76, v127
	v_mov_b32_e32 v123, v127
	v_mov_b32_e32 v122, v127
	v_mov_b32_e32 v121, v127
	v_mov_b32_e32 v120, v127
	v_mov_b32_e32 v119, v127
	v_mov_b32_e32 v118, v127
	v_mov_b32_e32 v117, v127
	v_mov_b32_e32 v116, v127
	v_mov_b32_e32 v107, v127
	v_mov_b32_e32 v106, v127
	v_mov_b32_e32 v105, v127
	v_mov_b32_e32 v104, v127
	v_mov_b32_e32 v103, v127
	v_mov_b32_e32 v102, v127
	v_mov_b32_e32 v101, v127
	v_mov_b32_e32 v100, v127
	v_mov_b32_e32 v91, v127
	v_mov_b32_e32 v90, v127
	v_mov_b32_e32 v89, v127
	v_mov_b32_e32 v88, v127
	v_mov_b32_e32 v87, v127
	v_mov_b32_e32 v86, v127
	v_mov_b32_e32 v85, v127
	v_mov_b32_e32 v84, v127
	v_mov_b32_e32 v75, v127
	v_mov_b32_e32 v74, v127
	v_mov_b32_e32 v73, v127
	v_mov_b32_e32 v72, v127
	v_mov_b32_e32 v71, v127
	v_mov_b32_e32 v70, v127
	v_mov_b32_e32 v69, v127
	v_mov_b32_e32 v68, v127
	v_mov_b32_e32 v67, v127
	v_mov_b32_e32 v66, v127
	v_mov_b32_e32 v65, v127
	v_mov_b32_e32 v64, v127
	v_mov_b32_e32 v63, v127
	v_mov_b32_e32 v62, v127
	v_mov_b32_e32 v61, v127
	v_mov_b32_e32 v60, v127
	v_mov_b32_e32 v51, v127
	v_mov_b32_e32 v50, v127
	v_mov_b32_e32 v49, v127
	v_mov_b32_e32 v48, v127
	v_mov_b32_e32 v47, v127
	v_mov_b32_e32 v46, v127
	v_mov_b32_e32 v45, v127
	v_mov_b32_e32 v44, v127
	v_mov_b32_e32 v35, v127
	v_mov_b32_e32 v34, v127
	v_mov_b32_e32 v33, v127
	v_mov_b32_e32 v32, v127
	v_mov_b32_e32 v31, v127
	v_mov_b32_e32 v30, v127
	v_mov_b32_e32 v29, v127
	v_mov_b32_e32 v28, v127
	v_mov_b32_e32 v19, v127
	v_mov_b32_e32 v18, v127
	v_mov_b32_e32 v17, v127
	v_mov_b32_e32 v16, v127
	v_mov_b32_e32 v15, v127
	v_mov_b32_e32 v14, v127
	v_mov_b32_e32 v13, v127
	v_mov_b32_e32 v12, v127
	v_mov_b32_e32 v59, v127
	v_mov_b32_e32 v58, v127
	v_mov_b32_e32 v57, v127
	v_mov_b32_e32 v56, v127
	v_mov_b32_e32 v55, v127
	v_mov_b32_e32 v54, v127
	v_mov_b32_e32 v53, v127
	v_mov_b32_e32 v52, v127
	v_mov_b32_e32 v43, v127
	v_mov_b32_e32 v42, v127
	v_mov_b32_e32 v41, v127
	v_mov_b32_e32 v40, v127
	v_mov_b32_e32 v39, v127
	v_mov_b32_e32 v38, v127
	v_mov_b32_e32 v37, v127
	v_mov_b32_e32 v36, v127
	v_mov_b32_e32 v27, v127
	v_mov_b32_e32 v26, v127
	v_mov_b32_e32 v25, v127
	v_mov_b32_e32 v24, v127
	v_mov_b32_e32 v23, v127
	v_mov_b32_e32 v22, v127
	v_mov_b32_e32 v21, v127
	v_mov_b32_e32 v20, v127
	v_mov_b32_e32 v11, v127
	v_mov_b32_e32 v10, v127
	v_mov_b32_e32 v9, v127
	v_mov_b32_e32 v8, v127
	v_mov_b32_e32 v7, v127
	v_mov_b32_e32 v6, v127
	v_mov_b32_e32 v5, v127
	v_mov_b32_e32 v4, v127
	s_branch .LBB0_623
.Lkz_3:
	s_and_b64 s[40:41], s[38:39], exec
	s_cselect_b32 s3, s25, s31
	s_cselect_b32 s21, s24, s30
	s_cselect_b32 s23, s27, s29
	s_cselect_b32 s66, s26, s28
	s_add_u32 s67, s30, 0x100
	s_addc_u32 s68, s31, 0
	s_add_u32 s69, s28, 0x100
	v_mov_b32_e32 v4, 0
	s_addc_u32 s70, s29, 0
	s_mov_b32 s28, 0
	v_mov_b32_e32 v5, v4
	v_mov_b32_e32 v6, v4
	v_mov_b32_e32 v7, v4
	v_mov_b32_e32 v8, v4
	v_mov_b32_e32 v9, v4
	v_mov_b32_e32 v10, v4
	v_mov_b32_e32 v11, v4
	v_mov_b32_e32 v20, v4
	v_mov_b32_e32 v21, v4
	v_mov_b32_e32 v22, v4
	v_mov_b32_e32 v23, v4
	v_mov_b32_e32 v24, v4
	v_mov_b32_e32 v25, v4
	v_mov_b32_e32 v26, v4
	v_mov_b32_e32 v27, v4
	v_mov_b32_e32 v36, v4
	v_mov_b32_e32 v37, v4
	v_mov_b32_e32 v38, v4
	v_mov_b32_e32 v39, v4
	v_mov_b32_e32 v40, v4
	v_mov_b32_e32 v41, v4
	v_mov_b32_e32 v42, v4
	v_mov_b32_e32 v43, v4
	v_mov_b32_e32 v52, v4
	v_mov_b32_e32 v53, v4
	v_mov_b32_e32 v54, v4
	v_mov_b32_e32 v55, v4
	v_mov_b32_e32 v56, v4
	v_mov_b32_e32 v57, v4
	v_mov_b32_e32 v58, v4
	v_mov_b32_e32 v59, v4
	v_mov_b32_e32 v12, v4
	v_mov_b32_e32 v13, v4
	v_mov_b32_e32 v14, v4
	v_mov_b32_e32 v15, v4
	v_mov_b32_e32 v16, v4
	v_mov_b32_e32 v17, v4
	v_mov_b32_e32 v18, v4
	v_mov_b32_e32 v19, v4
	v_mov_b32_e32 v28, v4
	v_mov_b32_e32 v29, v4
	v_mov_b32_e32 v30, v4
	v_mov_b32_e32 v31, v4
	v_mov_b32_e32 v32, v4
	v_mov_b32_e32 v33, v4
	v_mov_b32_e32 v34, v4
	v_mov_b32_e32 v35, v4
	v_mov_b32_e32 v44, v4
	v_mov_b32_e32 v45, v4
	v_mov_b32_e32 v46, v4
	v_mov_b32_e32 v47, v4
	v_mov_b32_e32 v48, v4
	v_mov_b32_e32 v49, v4
	v_mov_b32_e32 v50, v4
	v_mov_b32_e32 v51, v4
	v_mov_b32_e32 v60, v4
	v_mov_b32_e32 v61, v4
	v_mov_b32_e32 v62, v4
	v_mov_b32_e32 v63, v4
	v_mov_b32_e32 v64, v4
	v_mov_b32_e32 v65, v4
	v_mov_b32_e32 v66, v4
	v_mov_b32_e32 v67, v4
	v_mov_b32_e32 v68, v4
	v_mov_b32_e32 v69, v4
	v_mov_b32_e32 v70, v4
	v_mov_b32_e32 v71, v4
	v_mov_b32_e32 v72, v4
	v_mov_b32_e32 v73, v4
	v_mov_b32_e32 v74, v4
	v_mov_b32_e32 v75, v4
	v_mov_b32_e32 v84, v4
	v_mov_b32_e32 v85, v4
	v_mov_b32_e32 v86, v4
	v_mov_b32_e32 v87, v4
	v_mov_b32_e32 v88, v4
	v_mov_b32_e32 v89, v4
	v_mov_b32_e32 v90, v4
	v_mov_b32_e32 v91, v4
	v_mov_b32_e32 v100, v4
	v_mov_b32_e32 v101, v4
	v_mov_b32_e32 v102, v4
	v_mov_b32_e32 v103, v4
	v_mov_b32_e32 v104, v4
	v_mov_b32_e32 v105, v4
	v_mov_b32_e32 v106, v4
	v_mov_b32_e32 v107, v4
	v_mov_b32_e32 v116, v4
	v_mov_b32_e32 v117, v4
	v_mov_b32_e32 v118, v4
	v_mov_b32_e32 v119, v4
	v_mov_b32_e32 v120, v4
	v_mov_b32_e32 v121, v4
	v_mov_b32_e32 v122, v4
	v_mov_b32_e32 v123, v4
	v_mov_b32_e32 v76, v4
	v_mov_b32_e32 v77, v4
	v_mov_b32_e32 v78, v4
	v_mov_b32_e32 v79, v4
	v_mov_b32_e32 v80, v4
	v_mov_b32_e32 v81, v4
	v_mov_b32_e32 v82, v4
	v_mov_b32_e32 v83, v4
	v_mov_b32_e32 v92, v4
	v_mov_b32_e32 v93, v4
	v_mov_b32_e32 v94, v4
	v_mov_b32_e32 v95, v4
	v_mov_b32_e32 v96, v4
	v_mov_b32_e32 v97, v4
	v_mov_b32_e32 v98, v4
	v_mov_b32_e32 v99, v4
	v_mov_b32_e32 v108, v4
	v_mov_b32_e32 v109, v4
	v_mov_b32_e32 v110, v4
	v_mov_b32_e32 v111, v4
	v_mov_b32_e32 v112, v4
	v_mov_b32_e32 v113, v4
	v_mov_b32_e32 v114, v4
	v_mov_b32_e32 v115, v4
	v_mov_b32_e32 v128, v4
	v_mov_b32_e32 v129, v4
	v_mov_b32_e32 v130, v4
	v_mov_b32_e32 v131, v4
	v_mov_b32_e32 v124, v4
	v_mov_b32_e32 v125, v4
	v_mov_b32_e32 v126, v4
	v_mov_b32_e32 v127, v4

.LBB0_1019:
	s_ashr_i32 s19, s18, 31
	s_lshl_b64 s[0:1], s[18:19], 20
	s_add_u32 s20, s41, s0
	s_addc_u32 s21, s42, s1
	s_ashr_i32 s13, s12, 31
	s_lshl_b64 s[0:1], s[12:13], 20
	s_add_u32 s22, s43, s0
	v_mov_b32_e32 v131, 0
	s_addc_u32 s23, s48, s1
	s_andn2_b64 vcc, exec, s[8:9]
	s_cbranch_vccz .Lkz_4
	v_mov_b32_e32 v130, v131
	v_mov_b32_e32 v129, v131
	v_mov_b32_e32 v128, v131
	v_mov_b32_e32 v127, v131
	v_mov_b32_e32 v126, v131
	v_mov_b32_e32 v125, v131
	v_mov_b32_e32 v124, v131
	v_mov_b32_e32 v115, v131
	v_mov_b32_e32 v114, v131
	v_mov_b32_e32 v113, v131
	v_mov_b32_e32 v112, v131
	v_mov_b32_e32 v111, v131
	v_mov_b32_e32 v110, v131
	v_mov_b32_e32 v109, v131
	v_mov_b32_e32 v108, v131
	v_mov_b32_e32 v99, v131
	v_mov_b32_e32 v98, v131
	v_mov_b32_e32 v97, v131
	v_mov_b32_e32 v96, v131
	v_mov_b32_e32 v95, v131
	v_mov_b32_e32 v94, v131
	v_mov_b32_e32 v93, v131
	v_mov_b32_e32 v92, v131
	v_mov_b32_e32 v83, v131
	v_mov_b32_e32 v82, v131
	v_mov_b32_e32 v81, v131
	v_mov_b32_e32 v80, v131
	v_mov_b32_e32 v79, v131
	v_mov_b32_e32 v78, v131
	v_mov_b32_e32 v77, v131
	v_mov_b32_e32 v76, v131
	v_mov_b32_e32 v123, v131
	v_mov_b32_e32 v122, v131
	v_mov_b32_e32 v121, v131
	v_mov_b32_e32 v120, v131
	v_mov_b32_e32 v119, v131
	v_mov_b32_e32 v118, v131
	v_mov_b32_e32 v117, v131
	v_mov_b32_e32 v116, v131
	v_mov_b32_e32 v107, v131
	v_mov_b32_e32 v106, v131
	v_mov_b32_e32 v105, v131
	v_mov_b32_e32 v104, v131
	v_mov_b32_e32 v103, v131
	v_mov_b32_e32 v102, v131
	v_mov_b32_e32 v101, v131
	v_mov_b32_e32 v100, v131
	v_mov_b32_e32 v91, v131
	v_mov_b32_e32 v90, v131
	v_mov_b32_e32 v89, v131
	v_mov_b32_e32 v88, v131
	v_mov_b32_e32 v87, v131
	v_mov_b32_e32 v86, v131
	v_mov_b32_e32 v85, v131
	v_mov_b32_e32 v84, v131
	v_mov_b32_e32 v75, v131
	v_mov_b32_e32 v74, v131
	v_mov_b32_e32 v73, v131
	v_mov_b32_e32 v72, v131
	v_mov_b32_e32 v71, v131
	v_mov_b32_e32 v70, v131
	v_mov_b32_e32 v69, v131
	v_mov_b32_e32 v68, v131
	v_mov_b32_e32 v67, v131
	v_mov_b32_e32 v66, v131
	v_mov_b32_e32 v65, v131
	v_mov_b32_e32 v64, v131
	v_mov_b32_e32 v63, v131
	v_mov_b32_e32 v62, v131
	v_mov_b32_e32 v61, v131
	v_mov_b32_e32 v60, v131
	v_mov_b32_e32 v51, v131
	v_mov_b32_e32 v50, v131
	v_mov_b32_e32 v49, v131
	v_mov_b32_e32 v48, v131
	v_mov_b32_e32 v47, v131
	v_mov_b32_e32 v46, v131
	v_mov_b32_e32 v45, v131
	v_mov_b32_e32 v44, v131
	v_mov_b32_e32 v35, v131
	v_mov_b32_e32 v34, v131
	v_mov_b32_e32 v33, v131
	v_mov_b32_e32 v32, v131
	v_mov_b32_e32 v31, v131
	v_mov_b32_e32 v30, v131
	v_mov_b32_e32 v29, v131
	v_mov_b32_e32 v28, v131
	v_mov_b32_e32 v19, v131
	v_mov_b32_e32 v18, v131
	v_mov_b32_e32 v17, v131
	v_mov_b32_e32 v16, v131
	v_mov_b32_e32 v15, v131
	v_mov_b32_e32 v14, v131
	v_mov_b32_e32 v13, v131
	v_mov_b32_e32 v12, v131
	v_mov_b32_e32 v59, v131
	v_mov_b32_e32 v58, v131
	v_mov_b32_e32 v57, v131
	v_mov_b32_e32 v56, v131
	v_mov_b32_e32 v55, v131
	v_mov_b32_e32 v54, v131
	v_mov_b32_e32 v53, v131
	v_mov_b32_e32 v52, v131
	v_mov_b32_e32 v43, v131
	v_mov_b32_e32 v42, v131
	v_mov_b32_e32 v41, v131
	v_mov_b32_e32 v40, v131
	v_mov_b32_e32 v39, v131
	v_mov_b32_e32 v38, v131
	v_mov_b32_e32 v37, v131
	v_mov_b32_e32 v36, v131
	v_mov_b32_e32 v27, v131
	v_mov_b32_e32 v26, v131
	v_mov_b32_e32 v25, v131
	v_mov_b32_e32 v24, v131
	v_mov_b32_e32 v23, v131
	v_mov_b32_e32 v22, v131
	v_mov_b32_e32 v21, v131
	v_mov_b32_e32 v20, v131
	v_mov_b32_e32 v11, v131
	v_mov_b32_e32 v10, v131
	v_mov_b32_e32 v9, v131
	v_mov_b32_e32 v8, v131
	v_mov_b32_e32 v7, v131
	v_mov_b32_e32 v6, v131
	v_mov_b32_e32 v5, v131
	v_mov_b32_e32 v4, v131
	s_branch .LBB0_1025
.Lkz_4:
	s_and_b64 s[0:1], s[38:39], exec
	s_cselect_b32 s1, s21, s29
	s_cselect_b32 s13, s20, s28
	s_cselect_b32 s14, s23, s3
	s_cselect_b32 s15, s22, s2
	s_ashr_i32 s25, s24, 31
	s_ashr_i32 s27, s26, 31
	s_lshl_b64 s[30:31], s[24:25], 22
	s_lshl_b64 s[34:35], s[26:27], 17
	s_add_u32 s30, s30, s34
	s_addc_u32 s31, s31, s35
	s_add_u32 s19, s28, 0x100
	s_addc_u32 s25, s29, 0
	s_add_u32 s27, s2, 0x100
	v_mov_b32_e32 v4, 0
	v_lshl_add_u64 v[180:181], v[186:187], 0, s[30:31]
	s_addc_u32 s33, s3, 0
	s_mov_b32 s0, 0
	v_mov_b32_e32 v5, v4
	v_mov_b32_e32 v6, v4
	v_mov_b32_e32 v7, v4
	v_mov_b32_e32 v8, v4
	v_mov_b32_e32 v9, v4
	v_mov_b32_e32 v10, v4
	v_mov_b32_e32 v11, v4
	v_mov_b32_e32 v20, v4
	v_mov_b32_e32 v21, v4
	v_mov_b32_e32 v22, v4
	v_mov_b32_e32 v23, v4
	v_mov_b32_e32 v24, v4
	v_mov_b32_e32 v25, v4
	v_mov_b32_e32 v26, v4
	v_mov_b32_e32 v27, v4
	v_mov_b32_e32 v36, v4
	v_mov_b32_e32 v37, v4
	v_mov_b32_e32 v38, v4
	v_mov_b32_e32 v39, v4
	v_mov_b32_e32 v40, v4
	v_mov_b32_e32 v41, v4
	v_mov_b32_e32 v42, v4
	v_mov_b32_e32 v43, v4
	v_mov_b32_e32 v52, v4
	v_mov_b32_e32 v53, v4
	v_mov_b32_e32 v54, v4
	v_mov_b32_e32 v55, v4
	v_mov_b32_e32 v56, v4
	v_mov_b32_e32 v57, v4
	v_mov_b32_e32 v58, v4
	v_mov_b32_e32 v59, v4
	v_mov_b32_e32 v12, v4
	v_mov_b32_e32 v13, v4
	v_mov_b32_e32 v14, v4
	v_mov_b32_e32 v15, v4
	v_mov_b32_e32 v16, v4
	v_mov_b32_e32 v17, v4
	v_mov_b32_e32 v18, v4
	v_mov_b32_e32 v19, v4
	v_mov_b32_e32 v28, v4
	v_mov_b32_e32 v29, v4
	v_mov_b32_e32 v30, v4
	v_mov_b32_e32 v31, v4
	v_mov_b32_e32 v32, v4
	v_mov_b32_e32 v33, v4
	v_mov_b32_e32 v34, v4
	v_mov_b32_e32 v35, v4
	v_mov_b32_e32 v44, v4
	v_mov_b32_e32 v45, v4
	v_mov_b32_e32 v46, v4
	v_mov_b32_e32 v47, v4
	v_mov_b32_e32 v48, v4
	v_mov_b32_e32 v49, v4
	v_mov_b32_e32 v50, v4
	v_mov_b32_e32 v51, v4
	v_mov_b32_e32 v60, v4
	v_mov_b32_e32 v61, v4
	v_mov_b32_e32 v62, v4
	v_mov_b32_e32 v63, v4
	v_mov_b32_e32 v64, v4
	v_mov_b32_e32 v65, v4
	v_mov_b32_e32 v66, v4
	v_mov_b32_e32 v67, v4
	v_mov_b32_e32 v68, v4
	v_mov_b32_e32 v69, v4
	v_mov_b32_e32 v70, v4
	v_mov_b32_e32 v71, v4
	v_mov_b32_e32 v72, v4
	v_mov_b32_e32 v73, v4
	v_mov_b32_e32 v74, v4
	v_mov_b32_e32 v75, v4
	v_mov_b32_e32 v84, v4
	v_mov_b32_e32 v85, v4
	v_mov_b32_e32 v86, v4
	v_mov_b32_e32 v87, v4
	v_mov_b32_e32 v88, v4
	v_mov_b32_e32 v89, v4
	v_mov_b32_e32 v90, v4
	v_mov_b32_e32 v91, v4
	v_mov_b32_e32 v100, v4
	v_mov_b32_e32 v101, v4
	v_mov_b32_e32 v102, v4
	v_mov_b32_e32 v103, v4
	v_mov_b32_e32 v104, v4
	v_mov_b32_e32 v105, v4
	v_mov_b32_e32 v106, v4
	v_mov_b32_e32 v107, v4
	v_mov_b32_e32 v116, v4
	v_mov_b32_e32 v117, v4
	v_mov_b32_e32 v118, v4
	v_mov_b32_e32 v119, v4
	v_mov_b32_e32 v120, v4
	v_mov_b32_e32 v121, v4
	v_mov_b32_e32 v122, v4
	v_mov_b32_e32 v123, v4
	v_mov_b32_e32 v76, v4
	v_mov_b32_e32 v77, v4
	v_mov_b32_e32 v78, v4
	v_mov_b32_e32 v79, v4
	v_mov_b32_e32 v80, v4
	v_mov_b32_e32 v81, v4
	v_mov_b32_e32 v82, v4
	v_mov_b32_e32 v83, v4
	v_mov_b32_e32 v92, v4
	v_mov_b32_e32 v93, v4
	v_mov_b32_e32 v94, v4
	v_mov_b32_e32 v95, v4
	v_mov_b32_e32 v96, v4
	v_mov_b32_e32 v97, v4
	v_mov_b32_e32 v98, v4
	v_mov_b32_e32 v99, v4
	v_mov_b32_e32 v108, v4
	v_mov_b32_e32 v109, v4
	v_mov_b32_e32 v110, v4
	v_mov_b32_e32 v111, v4
	v_mov_b32_e32 v112, v4
	v_mov_b32_e32 v113, v4
	v_mov_b32_e32 v114, v4
	v_mov_b32_e32 v115, v4
	v_mov_b32_e32 v124, v4
	v_mov_b32_e32 v125, v4
	v_mov_b32_e32 v126, v4
	v_mov_b32_e32 v127, v4
	v_mov_b32_e32 v128, v4
	v_mov_b32_e32 v129, v4
	v_mov_b32_e32 v130, v4
	v_mov_b32_e32 v131, v4

.LBB0_1094:
	s_ashr_i32 s21, s20, 31
	s_lshl_b64 s[24:25], s[20:21], 20
	s_add_u32 s24, s14, s24
	s_addc_u32 s25, s15, s25
	s_ashr_i32 s3, s2, 31
	s_lshl_b64 s[26:27], s[2:3], 20
	s_add_u32 s26, s17, s26
	v_mov_b32_e32 v127, 0
	s_addc_u32 s27, s33, s27
	s_andn2_b64 vcc, exec, s[12:13]
	s_cbranch_vccz .Lkz_5
	v_mov_b32_e32 v126, v127
	v_mov_b32_e32 v125, v127
	v_mov_b32_e32 v124, v127
	v_mov_b32_e32 v131, v127
	v_mov_b32_e32 v130, v127
	v_mov_b32_e32 v129, v127
	v_mov_b32_e32 v128, v127
	v_mov_b32_e32 v115, v127
	v_mov_b32_e32 v114, v127
	v_mov_b32_e32 v113, v127
	v_mov_b32_e32 v112, v127
	v_mov_b32_e32 v111, v127
	v_mov_b32_e32 v110, v127
	v_mov_b32_e32 v109, v127
	v_mov_b32_e32 v108, v127
	v_mov_b32_e32 v99, v127
	v_mov_b32_e32 v98, v127
	v_mov_b32_e32 v97, v127
	v_mov_b32_e32 v96, v127
	v_mov_b32_e32 v95, v127
	v_mov_b32_e32 v94, v127
	v_mov_b32_e32 v93, v127
	v_mov_b32_e32 v92, v127
	v_mov_b32_e32 v83, v127
	v_mov_b32_e32 v82, v127
	v_mov_b32_e32 v81, v127
	v_mov_b32_e32 v80, v127
	v_mov_b32_e32 v79, v127
	v_mov_b32_e32 v78, v127
	v_mov_b32_e32 v77, v127
	v_mov_b32_e32 v76, v127
	v_mov_b32_e32 v123, v127
	v_mov_b32_e32 v122, v127
	v_mov_b32_e32 v121, v127
	v_mov_b32_e32 v120, v127
	v_mov_b32_e32 v119, v127
	v_mov_b32_e32 v118, v127
	v_mov_b32_e32 v117, v127
	v_mov_b32_e32 v116, v127
	v_mov_b32_e32 v107, v127
	v_mov_b32_e32 v106, v127
	v_mov_b32_e32 v105, v127
	v_mov_b32_e32 v104, v127
	v_mov_b32_e32 v103, v127
	v_mov_b32_e32 v102, v127
	v_mov_b32_e32 v101, v127
	v_mov_b32_e32 v100, v127
	v_mov_b32_e32 v91, v127
	v_mov_b32_e32 v90, v127
	v_mov_b32_e32 v89, v127
	v_mov_b32_e32 v88, v127
	v_mov_b32_e32 v87, v127
	v_mov_b32_e32 v86, v127
	v_mov_b32_e32 v85, v127
	v_mov_b32_e32 v84, v127
	v_mov_b32_e32 v75, v127
	v_mov_b32_e32 v74, v127
	v_mov_b32_e32 v73, v127
	v_mov_b32_e32 v72, v127
	v_mov_b32_e32 v71, v127
	v_mov_b32_e32 v70, v127
	v_mov_b32_e32 v69, v127
	v_mov_b32_e32 v68, v127
	v_mov_b32_e32 v67, v127
	v_mov_b32_e32 v66, v127
	v_mov_b32_e32 v65, v127
	v_mov_b32_e32 v64, v127
	v_mov_b32_e32 v63, v127
	v_mov_b32_e32 v62, v127
	v_mov_b32_e32 v61, v127
	v_mov_b32_e32 v60, v127
	v_mov_b32_e32 v51, v127
	v_mov_b32_e32 v50, v127
	v_mov_b32_e32 v49, v127
	v_mov_b32_e32 v48, v127
	v_mov_b32_e32 v47, v127
	v_mov_b32_e32 v46, v127
	v_mov_b32_e32 v45, v127
	v_mov_b32_e32 v44, v127
	v_mov_b32_e32 v35, v127
	v_mov_b32_e32 v34, v127
	v_mov_b32_e32 v33, v127
	v_mov_b32_e32 v32, v127
	v_mov_b32_e32 v31, v127
	v_mov_b32_e32 v30, v127
	v_mov_b32_e32 v29, v127
	v_mov_b32_e32 v28, v127
	v_mov_b32_e32 v19, v127
	v_mov_b32_e32 v18, v127
	v_mov_b32_e32 v17, v127
	v_mov_b32_e32 v16, v127
	v_mov_b32_e32 v15, v127
	v_mov_b32_e32 v14, v127
	v_mov_b32_e32 v13, v127
	v_mov_b32_e32 v12, v127
	v_mov_b32_e32 v59, v127
	v_mov_b32_e32 v58, v127
	v_mov_b32_e32 v57, v127
	v_mov_b32_e32 v56, v127
	v_mov_b32_e32 v55, v127
	v_mov_b32_e32 v54, v127
	v_mov_b32_e32 v53, v127
	v_mov_b32_e32 v52, v127
	v_mov_b32_e32 v43, v127
	v_mov_b32_e32 v42, v127
	v_mov_b32_e32 v41, v127
	v_mov_b32_e32 v40, v127
	v_mov_b32_e32 v39, v127
	v_mov_b32_e32 v38, v127
	v_mov_b32_e32 v37, v127
	v_mov_b32_e32 v36, v127
	v_mov_b32_e32 v27, v127
	v_mov_b32_e32 v26, v127
	v_mov_b32_e32 v25, v127
	v_mov_b32_e32 v24, v127
	v_mov_b32_e32 v23, v127
	v_mov_b32_e32 v22, v127
	v_mov_b32_e32 v21, v127
	v_mov_b32_e32 v20, v127
	v_mov_b32_e32 v11, v127
	v_mov_b32_e32 v10, v127
	v_mov_b32_e32 v9, v127
	v_mov_b32_e32 v8, v127
	v_mov_b32_e32 v7, v127
	v_mov_b32_e32 v6, v127
	v_mov_b32_e32 v5, v127
	v_mov_b32_e32 v4, v127
	s_branch .LBB0_1097
.Lkz_5:
	s_and_b64 s[38:39], s[4:5], exec
	s_cselect_b32 s3, s25, s31
	s_cselect_b32 s21, s24, s30
	s_cselect_b32 s65, s27, s29
	s_cselect_b32 s66, s26, s28
	s_add_u32 s67, s30, 0x100
	s_addc_u32 s68, s31, 0
	s_add_u32 s69, s28, 0x100
	s_addc_u32 s70, s29, 0
	s_add_u32 s28, s30, 0x80080
	v_mov_b32_e32 v4, 0
	s_addc_u32 s29, s31, 0
	s_mov_b32 s30, 0
	v_mov_b32_e32 v5, v4
	v_mov_b32_e32 v6, v4
	v_mov_b32_e32 v7, v4
	v_mov_b32_e32 v8, v4
	v_mov_b32_e32 v9, v4
	v_mov_b32_e32 v10, v4
	v_mov_b32_e32 v11, v4
	v_mov_b32_e32 v20, v4
	v_mov_b32_e32 v21, v4
	v_mov_b32_e32 v22, v4
	v_mov_b32_e32 v23, v4
	v_mov_b32_e32 v24, v4
	v_mov_b32_e32 v25, v4
	v_mov_b32_e32 v26, v4
	v_mov_b32_e32 v27, v4
	v_mov_b32_e32 v36, v4
	v_mov_b32_e32 v37, v4
	v_mov_b32_e32 v38, v4
	v_mov_b32_e32 v39, v4
	v_mov_b32_e32 v40, v4
	v_mov_b32_e32 v41, v4
	v_mov_b32_e32 v42, v4
	v_mov_b32_e32 v43, v4
	v_mov_b32_e32 v52, v4
	v_mov_b32_e32 v53, v4
	v_mov_b32_e32 v54, v4
	v_mov_b32_e32 v55, v4
	v_mov_b32_e32 v56, v4
	v_mov_b32_e32 v57, v4
	v_mov_b32_e32 v58, v4
	v_mov_b32_e32 v59, v4
	v_mov_b32_e32 v12, v4
	v_mov_b32_e32 v13, v4
	v_mov_b32_e32 v14, v4
	v_mov_b32_e32 v15, v4
	v_mov_b32_e32 v16, v4
	v_mov_b32_e32 v17, v4
	v_mov_b32_e32 v18, v4
	v_mov_b32_e32 v19, v4
	v_mov_b32_e32 v28, v4
	v_mov_b32_e32 v29, v4
	v_mov_b32_e32 v30, v4
	v_mov_b32_e32 v31, v4
	v_mov_b32_e32 v32, v4
	v_mov_b32_e32 v33, v4
	v_mov_b32_e32 v34, v4
	v_mov_b32_e32 v35, v4
	v_mov_b32_e32 v44, v4
	v_mov_b32_e32 v45, v4
	v_mov_b32_e32 v46, v4
	v_mov_b32_e32 v47, v4
	v_mov_b32_e32 v48, v4
	v_mov_b32_e32 v49, v4
	v_mov_b32_e32 v50, v4
	v_mov_b32_e32 v51, v4
	v_mov_b32_e32 v60, v4
	v_mov_b32_e32 v61, v4
	v_mov_b32_e32 v62, v4
	v_mov_b32_e32 v63, v4
	v_mov_b32_e32 v64, v4
	v_mov_b32_e32 v65, v4
	v_mov_b32_e32 v66, v4
	v_mov_b32_e32 v67, v4
	v_mov_b32_e32 v68, v4
	v_mov_b32_e32 v69, v4
	v_mov_b32_e32 v70, v4
	v_mov_b32_e32 v71, v4
	v_mov_b32_e32 v72, v4
	v_mov_b32_e32 v73, v4
	v_mov_b32_e32 v74, v4
	v_mov_b32_e32 v75, v4
	v_mov_b32_e32 v84, v4
	v_mov_b32_e32 v85, v4
	v_mov_b32_e32 v86, v4
	v_mov_b32_e32 v87, v4
	v_mov_b32_e32 v88, v4
	v_mov_b32_e32 v89, v4
	v_mov_b32_e32 v90, v4
	v_mov_b32_e32 v91, v4
	v_mov_b32_e32 v100, v4
	v_mov_b32_e32 v101, v4
	v_mov_b32_e32 v102, v4
	v_mov_b32_e32 v103, v4
	v_mov_b32_e32 v104, v4
	v_mov_b32_e32 v105, v4
	v_mov_b32_e32 v106, v4
	v_mov_b32_e32 v107, v4
	v_mov_b32_e32 v116, v4
	v_mov_b32_e32 v117, v4
	v_mov_b32_e32 v118, v4
	v_mov_b32_e32 v119, v4
	v_mov_b32_e32 v120, v4
	v_mov_b32_e32 v121, v4
	v_mov_b32_e32 v122, v4
	v_mov_b32_e32 v123, v4
	v_mov_b32_e32 v76, v4
	v_mov_b32_e32 v77, v4
	v_mov_b32_e32 v78, v4
	v_mov_b32_e32 v79, v4
	v_mov_b32_e32 v80, v4
	v_mov_b32_e32 v81, v4
	v_mov_b32_e32 v82, v4
	v_mov_b32_e32 v83, v4
	v_mov_b32_e32 v92, v4
	v_mov_b32_e32 v93, v4
	v_mov_b32_e32 v94, v4
	v_mov_b32_e32 v95, v4
	v_mov_b32_e32 v96, v4
	v_mov_b32_e32 v97, v4
	v_mov_b32_e32 v98, v4
	v_mov_b32_e32 v99, v4
	v_mov_b32_e32 v108, v4
	v_mov_b32_e32 v109, v4
	v_mov_b32_e32 v110, v4
	v_mov_b32_e32 v111, v4
	v_mov_b32_e32 v112, v4
	v_mov_b32_e32 v113, v4
	v_mov_b32_e32 v114, v4
	v_mov_b32_e32 v115, v4
	v_mov_b32_e32 v128, v4
	v_mov_b32_e32 v129, v4
	v_mov_b32_e32 v130, v4
	v_mov_b32_e32 v131, v4
	v_mov_b32_e32 v124, v4
	v_mov_b32_e32 v125, v4
	v_mov_b32_e32 v126, v4
	v_mov_b32_e32 v127, v4

.LBB0_1235:
	s_ashr_i32 s23, s22, 31
	s_lshl_b64 s[24:25], s[22:23], 20
	s_add_u32 s24, s15, s24
	s_addc_u32 s25, s17, s25
	s_ashr_i32 s21, s20, 31
	s_lshl_b64 s[26:27], s[20:21], 20
	s_add_u32 s26, s33, s26
	v_mov_b32_e32 v127, 0
	s_addc_u32 s27, s34, s27
	s_andn2_b64 vcc, exec, s[12:13]
	s_cbranch_vccz .Lkz_6
	v_mov_b32_e32 v126, v127
	v_mov_b32_e32 v125, v127
	v_mov_b32_e32 v124, v127
	v_mov_b32_e32 v131, v127
	v_mov_b32_e32 v130, v127
	v_mov_b32_e32 v129, v127
	v_mov_b32_e32 v128, v127
	v_mov_b32_e32 v115, v127
	v_mov_b32_e32 v114, v127
	v_mov_b32_e32 v113, v127
	v_mov_b32_e32 v112, v127
	v_mov_b32_e32 v111, v127
	v_mov_b32_e32 v110, v127
	v_mov_b32_e32 v109, v127
	v_mov_b32_e32 v108, v127
	v_mov_b32_e32 v99, v127
	v_mov_b32_e32 v98, v127
	v_mov_b32_e32 v97, v127
	v_mov_b32_e32 v96, v127
	v_mov_b32_e32 v95, v127
	v_mov_b32_e32 v94, v127
	v_mov_b32_e32 v93, v127
	v_mov_b32_e32 v92, v127
	v_mov_b32_e32 v83, v127
	v_mov_b32_e32 v82, v127
	v_mov_b32_e32 v81, v127
	v_mov_b32_e32 v80, v127
	v_mov_b32_e32 v79, v127
	v_mov_b32_e32 v78, v127
	v_mov_b32_e32 v77, v127
	v_mov_b32_e32 v76, v127
	v_mov_b32_e32 v123, v127
	v_mov_b32_e32 v122, v127
	v_mov_b32_e32 v121, v127
	v_mov_b32_e32 v120, v127
	v_mov_b32_e32 v119, v127
	v_mov_b32_e32 v118, v127
	v_mov_b32_e32 v117, v127
	v_mov_b32_e32 v116, v127
	v_mov_b32_e32 v107, v127
	v_mov_b32_e32 v106, v127
	v_mov_b32_e32 v105, v127
	v_mov_b32_e32 v104, v127
	v_mov_b32_e32 v103, v127
	v_mov_b32_e32 v102, v127
	v_mov_b32_e32 v101, v127
	v_mov_b32_e32 v100, v127
	v_mov_b32_e32 v91, v127
	v_mov_b32_e32 v90, v127
	v_mov_b32_e32 v89, v127
	v_mov_b32_e32 v88, v127
	v_mov_b32_e32 v87, v127
	v_mov_b32_e32 v86, v127
	v_mov_b32_e32 v85, v127
	v_mov_b32_e32 v84, v127
	v_mov_b32_e32 v75, v127
	v_mov_b32_e32 v74, v127
	v_mov_b32_e32 v73, v127
	v_mov_b32_e32 v72, v127
	v_mov_b32_e32 v71, v127
	v_mov_b32_e32 v70, v127
	v_mov_b32_e32 v69, v127
	v_mov_b32_e32 v68, v127
	v_mov_b32_e32 v67, v127
	v_mov_b32_e32 v66, v127
	v_mov_b32_e32 v65, v127
	v_mov_b32_e32 v64, v127
	v_mov_b32_e32 v63, v127
	v_mov_b32_e32 v62, v127
	v_mov_b32_e32 v61, v127
	v_mov_b32_e32 v60, v127
	v_mov_b32_e32 v51, v127
	v_mov_b32_e32 v50, v127
	v_mov_b32_e32 v49, v127
	v_mov_b32_e32 v48, v127
	v_mov_b32_e32 v47, v127
	v_mov_b32_e32 v46, v127
	v_mov_b32_e32 v45, v127
	v_mov_b32_e32 v44, v127
	v_mov_b32_e32 v35, v127
	v_mov_b32_e32 v34, v127
	v_mov_b32_e32 v33, v127
	v_mov_b32_e32 v32, v127
	v_mov_b32_e32 v31, v127
	v_mov_b32_e32 v30, v127
	v_mov_b32_e32 v29, v127
	v_mov_b32_e32 v28, v127
	v_mov_b32_e32 v19, v127
	v_mov_b32_e32 v18, v127
	v_mov_b32_e32 v17, v127
	v_mov_b32_e32 v16, v127
	v_mov_b32_e32 v15, v127
	v_mov_b32_e32 v14, v127
	v_mov_b32_e32 v13, v127
	v_mov_b32_e32 v12, v127
	v_mov_b32_e32 v59, v127
	v_mov_b32_e32 v58, v127
	v_mov_b32_e32 v57, v127
	v_mov_b32_e32 v56, v127
	v_mov_b32_e32 v55, v127
	v_mov_b32_e32 v54, v127
	v_mov_b32_e32 v53, v127
	v_mov_b32_e32 v52, v127
	v_mov_b32_e32 v43, v127
	v_mov_b32_e32 v42, v127
	v_mov_b32_e32 v41, v127
	v_mov_b32_e32 v40, v127
	v_mov_b32_e32 v39, v127
	v_mov_b32_e32 v38, v127
	v_mov_b32_e32 v37, v127
	v_mov_b32_e32 v36, v127
	v_mov_b32_e32 v27, v127
	v_mov_b32_e32 v26, v127
	v_mov_b32_e32 v25, v127
	v_mov_b32_e32 v24, v127
	v_mov_b32_e32 v23, v127
	v_mov_b32_e32 v22, v127
	v_mov_b32_e32 v21, v127
	v_mov_b32_e32 v20, v127
	v_mov_b32_e32 v11, v127
	v_mov_b32_e32 v10, v127
	v_mov_b32_e32 v9, v127
	v_mov_b32_e32 v8, v127
	v_mov_b32_e32 v7, v127
	v_mov_b32_e32 v6, v127
	v_mov_b32_e32 v5, v127
	v_mov_b32_e32 v4, v127
	s_branch .LBB0_1238
.Lkz_6:
	s_and_b64 s[38:39], s[4:5], exec
	s_cselect_b32 s21, s25, s31
	s_cselect_b32 s23, s24, s30
	s_cselect_b32 s63, s27, s29
	s_cselect_b32 s64, s26, s28
	s_add_u32 s65, s30, 0x100
	s_addc_u32 s66, s31, 0
	s_add_u32 s67, s28, 0x100
	v_mov_b32_e32 v4, 0
	s_addc_u32 s68, s29, 0
	s_mov_b32 s28, 0
	v_mov_b32_e32 v5, v4
	v_mov_b32_e32 v6, v4
	v_mov_b32_e32 v7, v4
	v_mov_b32_e32 v8, v4
	v_mov_b32_e32 v9, v4
	v_mov_b32_e32 v10, v4
	v_mov_b32_e32 v11, v4
	v_mov_b32_e32 v20, v4
	v_mov_b32_e32 v21, v4
	v_mov_b32_e32 v22, v4
	v_mov_b32_e32 v23, v4
	v_mov_b32_e32 v24, v4
	v_mov_b32_e32 v25, v4
	v_mov_b32_e32 v26, v4
	v_mov_b32_e32 v27, v4
	v_mov_b32_e32 v36, v4
	v_mov_b32_e32 v37, v4
	v_mov_b32_e32 v38, v4
	v_mov_b32_e32 v39, v4
	v_mov_b32_e32 v40, v4
	v_mov_b32_e32 v41, v4
	v_mov_b32_e32 v42, v4
	v_mov_b32_e32 v43, v4
	v_mov_b32_e32 v52, v4
	v_mov_b32_e32 v53, v4
	v_mov_b32_e32 v54, v4
	v_mov_b32_e32 v55, v4
	v_mov_b32_e32 v56, v4
	v_mov_b32_e32 v57, v4
	v_mov_b32_e32 v58, v4
	v_mov_b32_e32 v59, v4
	v_mov_b32_e32 v12, v4
	v_mov_b32_e32 v13, v4
	v_mov_b32_e32 v14, v4
	v_mov_b32_e32 v15, v4
	v_mov_b32_e32 v16, v4
	v_mov_b32_e32 v17, v4
	v_mov_b32_e32 v18, v4
	v_mov_b32_e32 v19, v4
	v_mov_b32_e32 v28, v4
	v_mov_b32_e32 v29, v4
	v_mov_b32_e32 v30, v4
	v_mov_b32_e32 v31, v4
	v_mov_b32_e32 v32, v4
	v_mov_b32_e32 v33, v4
	v_mov_b32_e32 v34, v4
	v_mov_b32_e32 v35, v4
	v_mov_b32_e32 v44, v4
	v_mov_b32_e32 v45, v4
	v_mov_b32_e32 v46, v4
	v_mov_b32_e32 v47, v4
	v_mov_b32_e32 v48, v4
	v_mov_b32_e32 v49, v4
	v_mov_b32_e32 v50, v4
	v_mov_b32_e32 v51, v4
	v_mov_b32_e32 v60, v4
	v_mov_b32_e32 v61, v4
	v_mov_b32_e32 v62, v4
	v_mov_b32_e32 v63, v4
	v_mov_b32_e32 v64, v4
	v_mov_b32_e32 v65, v4
	v_mov_b32_e32 v66, v4
	v_mov_b32_e32 v67, v4
	v_mov_b32_e32 v68, v4
	v_mov_b32_e32 v69, v4
	v_mov_b32_e32 v70, v4
	v_mov_b32_e32 v71, v4
	v_mov_b32_e32 v72, v4
	v_mov_b32_e32 v73, v4
	v_mov_b32_e32 v74, v4
	v_mov_b32_e32 v75, v4
	v_mov_b32_e32 v84, v4
	v_mov_b32_e32 v85, v4
	v_mov_b32_e32 v86, v4
	v_mov_b32_e32 v87, v4
	v_mov_b32_e32 v88, v4
	v_mov_b32_e32 v89, v4
	v_mov_b32_e32 v90, v4
	v_mov_b32_e32 v91, v4
	v_mov_b32_e32 v100, v4
	v_mov_b32_e32 v101, v4
	v_mov_b32_e32 v102, v4
	v_mov_b32_e32 v103, v4
	v_mov_b32_e32 v104, v4
	v_mov_b32_e32 v105, v4
	v_mov_b32_e32 v106, v4
	v_mov_b32_e32 v107, v4
	v_mov_b32_e32 v116, v4
	v_mov_b32_e32 v117, v4
	v_mov_b32_e32 v118, v4
	v_mov_b32_e32 v119, v4
	v_mov_b32_e32 v120, v4
	v_mov_b32_e32 v121, v4
	v_mov_b32_e32 v122, v4
	v_mov_b32_e32 v123, v4
	v_mov_b32_e32 v76, v4
	v_mov_b32_e32 v77, v4
	v_mov_b32_e32 v78, v4
	v_mov_b32_e32 v79, v4
	v_mov_b32_e32 v80, v4
	v_mov_b32_e32 v81, v4
	v_mov_b32_e32 v82, v4
	v_mov_b32_e32 v83, v4
	v_mov_b32_e32 v92, v4
	v_mov_b32_e32 v93, v4
	v_mov_b32_e32 v94, v4
	v_mov_b32_e32 v95, v4
	v_mov_b32_e32 v96, v4
	v_mov_b32_e32 v97, v4
	v_mov_b32_e32 v98, v4
	v_mov_b32_e32 v99, v4
	v_mov_b32_e32 v108, v4
	v_mov_b32_e32 v109, v4
	v_mov_b32_e32 v110, v4
	v_mov_b32_e32 v111, v4
	v_mov_b32_e32 v112, v4
	v_mov_b32_e32 v113, v4
	v_mov_b32_e32 v114, v4
	v_mov_b32_e32 v115, v4
	v_mov_b32_e32 v128, v4
	v_mov_b32_e32 v129, v4
	v_mov_b32_e32 v130, v4
	v_mov_b32_e32 v131, v4
	v_mov_b32_e32 v124, v4
	v_mov_b32_e32 v125, v4
	v_mov_b32_e32 v126, v4
	v_mov_b32_e32 v127, v4

.LBB0_1307:
	s_ashr_i32 s21, s20, 31
	s_lshl_b64 s[24:25], s[20:21], 22
	s_add_u32 s24, s14, s24
	s_addc_u32 s25, s15, s25
	s_ashr_i32 s3, s2, 31
	s_lshl_b64 s[26:27], s[2:3], 22
	s_add_u32 s26, s17, s26
	v_mov_b32_e32 v127, 0
	s_addc_u32 s27, s33, s27
	s_andn2_b64 vcc, exec, s[12:13]
	s_cbranch_vccz .Lkz_7
	v_mov_b32_e32 v126, v127
	v_mov_b32_e32 v125, v127
	v_mov_b32_e32 v124, v127
	v_mov_b32_e32 v131, v127
	v_mov_b32_e32 v130, v127
	v_mov_b32_e32 v129, v127
	v_mov_b32_e32 v128, v127
	v_mov_b32_e32 v115, v127
	v_mov_b32_e32 v114, v127
	v_mov_b32_e32 v113, v127
	v_mov_b32_e32 v112, v127
	v_mov_b32_e32 v111, v127
	v_mov_b32_e32 v110, v127
	v_mov_b32_e32 v109, v127
	v_mov_b32_e32 v108, v127
	v_mov_b32_e32 v99, v127
	v_mov_b32_e32 v98, v127
	v_mov_b32_e32 v97, v127
	v_mov_b32_e32 v96, v127
	v_mov_b32_e32 v95, v127
	v_mov_b32_e32 v94, v127
	v_mov_b32_e32 v93, v127
	v_mov_b32_e32 v92, v127
	v_mov_b32_e32 v83, v127
	v_mov_b32_e32 v82, v127
	v_mov_b32_e32 v81, v127
	v_mov_b32_e32 v80, v127
	v_mov_b32_e32 v79, v127
	v_mov_b32_e32 v78, v127
	v_mov_b32_e32 v77, v127
	v_mov_b32_e32 v76, v127
	v_mov_b32_e32 v123, v127
	v_mov_b32_e32 v122, v127
	v_mov_b32_e32 v121, v127
	v_mov_b32_e32 v120, v127
	v_mov_b32_e32 v119, v127
	v_mov_b32_e32 v118, v127
	v_mov_b32_e32 v117, v127
	v_mov_b32_e32 v116, v127
	v_mov_b32_e32 v107, v127
	v_mov_b32_e32 v106, v127
	v_mov_b32_e32 v105, v127
	v_mov_b32_e32 v104, v127
	v_mov_b32_e32 v103, v127
	v_mov_b32_e32 v102, v127
	v_mov_b32_e32 v101, v127
	v_mov_b32_e32 v100, v127
	v_mov_b32_e32 v91, v127
	v_mov_b32_e32 v90, v127
	v_mov_b32_e32 v89, v127
	v_mov_b32_e32 v88, v127
	v_mov_b32_e32 v87, v127
	v_mov_b32_e32 v86, v127
	v_mov_b32_e32 v85, v127
	v_mov_b32_e32 v84, v127
	v_mov_b32_e32 v75, v127
	v_mov_b32_e32 v74, v127
	v_mov_b32_e32 v73, v127
	v_mov_b32_e32 v72, v127
	v_mov_b32_e32 v71, v127
	v_mov_b32_e32 v70, v127
	v_mov_b32_e32 v69, v127
	v_mov_b32_e32 v68, v127
	v_mov_b32_e32 v67, v127
	v_mov_b32_e32 v66, v127
	v_mov_b32_e32 v65, v127
	v_mov_b32_e32 v64, v127
	v_mov_b32_e32 v63, v127
	v_mov_b32_e32 v62, v127
	v_mov_b32_e32 v61, v127
	v_mov_b32_e32 v60, v127
	v_mov_b32_e32 v51, v127
	v_mov_b32_e32 v50, v127
	v_mov_b32_e32 v49, v127
	v_mov_b32_e32 v48, v127
	v_mov_b32_e32 v47, v127
	v_mov_b32_e32 v46, v127
	v_mov_b32_e32 v45, v127
	v_mov_b32_e32 v44, v127
	v_mov_b32_e32 v35, v127
	v_mov_b32_e32 v34, v127
	v_mov_b32_e32 v33, v127
	v_mov_b32_e32 v32, v127
	v_mov_b32_e32 v31, v127
	v_mov_b32_e32 v30, v127
	v_mov_b32_e32 v29, v127
	v_mov_b32_e32 v28, v127
	v_mov_b32_e32 v19, v127
	v_mov_b32_e32 v18, v127
	v_mov_b32_e32 v17, v127
	v_mov_b32_e32 v16, v127
	v_mov_b32_e32 v15, v127
	v_mov_b32_e32 v14, v127
	v_mov_b32_e32 v13, v127
	v_mov_b32_e32 v12, v127
	v_mov_b32_e32 v59, v127
	v_mov_b32_e32 v58, v127
	v_mov_b32_e32 v57, v127
	v_mov_b32_e32 v56, v127
	v_mov_b32_e32 v55, v127
	v_mov_b32_e32 v54, v127
	v_mov_b32_e32 v53, v127
	v_mov_b32_e32 v52, v127
	v_mov_b32_e32 v43, v127
	v_mov_b32_e32 v42, v127
	v_mov_b32_e32 v41, v127
	v_mov_b32_e32 v40, v127
	v_mov_b32_e32 v39, v127
	v_mov_b32_e32 v38, v127
	v_mov_b32_e32 v37, v127
	v_mov_b32_e32 v36, v127
	v_mov_b32_e32 v27, v127
	v_mov_b32_e32 v26, v127
	v_mov_b32_e32 v25, v127
	v_mov_b32_e32 v24, v127
	v_mov_b32_e32 v23, v127
	v_mov_b32_e32 v22, v127
	v_mov_b32_e32 v21, v127
	v_mov_b32_e32 v20, v127
	v_mov_b32_e32 v11, v127
	v_mov_b32_e32 v10, v127
	v_mov_b32_e32 v9, v127
	v_mov_b32_e32 v8, v127
	v_mov_b32_e32 v7, v127
	v_mov_b32_e32 v6, v127
	v_mov_b32_e32 v5, v127
	v_mov_b32_e32 v4, v127
	s_branch .LBB0_1310
.Lkz_7:
	s_and_b64 s[38:39], s[4:5], exec
	s_cselect_b32 s3, s25, s31
	s_cselect_b32 s21, s24, s30
	s_cselect_b32 s65, s27, s29
	s_cselect_b32 s66, s26, s28
	s_add_u32 s67, s30, 0x100
	s_addc_u32 s68, s31, 0
	s_add_u32 s69, s28, 0x100
	s_addc_u32 s70, s29, 0
	s_add_u32 s28, s30, 0x200080
	v_mov_b32_e32 v4, 0
	s_addc_u32 s29, s31, 0
	s_mov_b32 s30, 0
	v_mov_b32_e32 v5, v4
	v_mov_b32_e32 v6, v4
	v_mov_b32_e32 v7, v4
	v_mov_b32_e32 v8, v4
	v_mov_b32_e32 v9, v4
	v_mov_b32_e32 v10, v4
	v_mov_b32_e32 v11, v4
	v_mov_b32_e32 v20, v4
	v_mov_b32_e32 v21, v4
	v_mov_b32_e32 v22, v4
	v_mov_b32_e32 v23, v4
	v_mov_b32_e32 v24, v4
	v_mov_b32_e32 v25, v4
	v_mov_b32_e32 v26, v4
	v_mov_b32_e32 v27, v4
	v_mov_b32_e32 v36, v4
	v_mov_b32_e32 v37, v4
	v_mov_b32_e32 v38, v4
	v_mov_b32_e32 v39, v4
	v_mov_b32_e32 v40, v4
	v_mov_b32_e32 v41, v4
	v_mov_b32_e32 v42, v4
	v_mov_b32_e32 v43, v4
	v_mov_b32_e32 v52, v4
	v_mov_b32_e32 v53, v4
	v_mov_b32_e32 v54, v4
	v_mov_b32_e32 v55, v4
	v_mov_b32_e32 v56, v4
	v_mov_b32_e32 v57, v4
	v_mov_b32_e32 v58, v4
	v_mov_b32_e32 v59, v4
	v_mov_b32_e32 v12, v4
	v_mov_b32_e32 v13, v4
	v_mov_b32_e32 v14, v4
	v_mov_b32_e32 v15, v4
	v_mov_b32_e32 v16, v4
	v_mov_b32_e32 v17, v4
	v_mov_b32_e32 v18, v4
	v_mov_b32_e32 v19, v4
	v_mov_b32_e32 v28, v4
	v_mov_b32_e32 v29, v4
	v_mov_b32_e32 v30, v4
	v_mov_b32_e32 v31, v4
	v_mov_b32_e32 v32, v4
	v_mov_b32_e32 v33, v4
	v_mov_b32_e32 v34, v4
	v_mov_b32_e32 v35, v4
	v_mov_b32_e32 v44, v4
	v_mov_b32_e32 v45, v4
	v_mov_b32_e32 v46, v4
	v_mov_b32_e32 v47, v4
	v_mov_b32_e32 v48, v4
	v_mov_b32_e32 v49, v4
	v_mov_b32_e32 v50, v4
	v_mov_b32_e32 v51, v4
	v_mov_b32_e32 v60, v4
	v_mov_b32_e32 v61, v4
	v_mov_b32_e32 v62, v4
	v_mov_b32_e32 v63, v4
	v_mov_b32_e32 v64, v4
	v_mov_b32_e32 v65, v4
	v_mov_b32_e32 v66, v4
	v_mov_b32_e32 v67, v4
	v_mov_b32_e32 v68, v4
	v_mov_b32_e32 v69, v4
	v_mov_b32_e32 v70, v4
	v_mov_b32_e32 v71, v4
	v_mov_b32_e32 v72, v4
	v_mov_b32_e32 v73, v4
	v_mov_b32_e32 v74, v4
	v_mov_b32_e32 v75, v4
	v_mov_b32_e32 v84, v4
	v_mov_b32_e32 v85, v4
	v_mov_b32_e32 v86, v4
	v_mov_b32_e32 v87, v4
	v_mov_b32_e32 v88, v4
	v_mov_b32_e32 v89, v4
	v_mov_b32_e32 v90, v4
	v_mov_b32_e32 v91, v4
	v_mov_b32_e32 v100, v4
	v_mov_b32_e32 v101, v4
	v_mov_b32_e32 v102, v4
	v_mov_b32_e32 v103, v4
	v_mov_b32_e32 v104, v4
	v_mov_b32_e32 v105, v4
	v_mov_b32_e32 v106, v4
	v_mov_b32_e32 v107, v4
	v_mov_b32_e32 v116, v4
	v_mov_b32_e32 v117, v4
	v_mov_b32_e32 v118, v4
	v_mov_b32_e32 v119, v4
	v_mov_b32_e32 v120, v4
	v_mov_b32_e32 v121, v4
	v_mov_b32_e32 v122, v4
	v_mov_b32_e32 v123, v4
	v_mov_b32_e32 v76, v4
	v_mov_b32_e32 v77, v4
	v_mov_b32_e32 v78, v4
	v_mov_b32_e32 v79, v4
	v_mov_b32_e32 v80, v4
	v_mov_b32_e32 v81, v4
	v_mov_b32_e32 v82, v4
	v_mov_b32_e32 v83, v4
	v_mov_b32_e32 v92, v4
	v_mov_b32_e32 v93, v4
	v_mov_b32_e32 v94, v4
	v_mov_b32_e32 v95, v4
	v_mov_b32_e32 v96, v4
	v_mov_b32_e32 v97, v4
	v_mov_b32_e32 v98, v4
	v_mov_b32_e32 v99, v4
	v_mov_b32_e32 v108, v4
	v_mov_b32_e32 v109, v4
	v_mov_b32_e32 v110, v4
	v_mov_b32_e32 v111, v4
	v_mov_b32_e32 v112, v4
	v_mov_b32_e32 v113, v4
	v_mov_b32_e32 v114, v4
	v_mov_b32_e32 v115, v4
	v_mov_b32_e32 v128, v4
	v_mov_b32_e32 v129, v4
	v_mov_b32_e32 v130, v4
	v_mov_b32_e32 v131, v4
	v_mov_b32_e32 v124, v4
	v_mov_b32_e32 v125, v4
	v_mov_b32_e32 v126, v4
	v_mov_b32_e32 v127, v4
